# GLA chain: decayed keys and chunk decays read with sc1 loads, acquire fence after the prep-done event dropped
# baseline (speedup 1.0000x reference)
.LBB0_1076:
	global_load_dword v0, v209, s[80:81] sc1
	s_movk_i32 s6, 0xbf
	s_waitcnt vmcnt(0)
	v_cmp_lt_u32_e32 vcc, s6, v0
	s_mov_b64 s[6:7], -1
	s_cbranch_vccnz .LBB0_1075
	s_sleep 2
	global_load_dword v0, v209, s[80:81] sc1
	s_movk_i32 s6, 0xc0
	s_waitcnt vmcnt(0)
	v_cmp_gt_u32_e32 vcc, s6, v0
	s_mov_b64 s[6:7], -1
	s_cbranch_vccz .LBB0_1075
	s_sleep 2
	global_load_dword v0, v209, s[80:81] sc1
	s_movk_i32 s6, 0xc0
	s_waitcnt vmcnt(0)
	v_cmp_gt_u32_e32 vcc, s6, v0
	s_mov_b64 s[6:7], -1
	s_cbranch_vccz .LBB0_1075
	s_sleep 2
	global_load_dword v0, v209, s[80:81] sc1
	s_movk_i32 s6, 0xc0
	s_waitcnt vmcnt(0)
	v_cmp_gt_u32_e32 vcc, s6, v0
	s_mov_b64 s[6:7], -1
	s_cbranch_vccz .LBB0_1075
	s_sleep 2
	global_load_dword v0, v209, s[80:81] sc1
	s_movk_i32 s6, 0xc0
	s_waitcnt vmcnt(0)
	v_cmp_gt_u32_e32 vcc, s6, v0
	s_mov_b64 s[6:7], -1
	s_cbranch_vccz .LBB0_1075
	s_add_i32 s8, s8, -5
	s_cmp_eq_u32 s8, 0
	s_cselect_b64 s[6:7], -1, 0
	s_sleep 2
	s_branch .LBB0_1075
.LBB0_1082:
	s_waitcnt vmcnt(0)
.LBB0_1083:
	s_or_b64 exec, exec, s[4:5]
	s_barrier
.LBB0_1084:
	s_mov_b64 s[6:7], s[0:1]
	v_mov_b32_e32 v12, v226
	s_load_dwordx2 s[4:5], s[6:7], 0x38
	s_nop 0
	s_load_dwordx2 s[6:7], s[6:7], 0x58
	v_readfirstlane_b32 s31, v12
	s_lshl_b32 s26, s86, 12
	s_ashr_i32 s40, s31, 6
	v_ashrrev_i32_e32 v126, 3, v12
	s_waitcnt lgkmcnt(0)
	s_add_u32 s8, s6, 0xb400000
	s_addc_u32 s9, s7, 0
	v_readlane_b32 s23, v254, 34
	v_lshlrev_b32_e32 v0, 6, v126
	s_add_u32 s38, s6, s23
	v_ashrrev_i32_e32 v1, 31, v0
	v_and_b32_e32 v127, 7, v12
	s_addc_u32 s39, s7, 0
	v_lshlrev_b64 v[116:117], 1, v[0:1]
	v_lshl_add_u64 v[0:1], s[38:39], 0, v[116:117]
	v_lshlrev_b32_e32 v208, 4, v127
	v_readlane_b32 s23, v254, 16
	v_lshl_add_u64 v[64:65], v[0:1], 0, v[208:209]
	v_and_b32_e32 v2, 31, v12
	v_add_u32_e32 v0, s23, v126
	v_readlane_b32 s23, v254, 37
	v_ashrrev_i32_e32 v1, 31, v0
	s_add_u32 s38, s6, s23
	s_addc_u32 s39, s7, 0
	v_lshlrev_b64 v[118:119], 7, v[0:1]
	v_lshl_add_u64 v[0:1], s[38:39], 0, v[118:119]
	s_ashr_i32 s38, s31, 2
	v_lshl_add_u64 v[66:67], v[0:1], 0, v[208:209]
	s_and_b32 s23, s38, 0xffffffe0
	v_mov_b32_e32 v0, s38
	s_movk_i32 s38, 0xffe0
	v_bfi_b32 v0, s38, v0, v12
	s_lshl_b32 s38, s40, 5
	v_bfe_u32 v86, v12, 5, 1
	v_and_or_b32 v87, s38, 32, v2
	v_and_b32_e32 v132, 15, v12
	v_mul_lo_u32 v30, v0, s49
	v_lshlrev_b32_e32 v31, 3, v86
	v_mul_u32_u24_e32 v0, 0x48, v87
	s_lshl_b32 s38, s40, 4
	v_readlane_b32 s39, v254, 15
	v_add_lshl_u32 v145, v0, v31, 1
	s_and_b32 s38, s38, 48
	v_or_b32_e32 v0, s39, v132
	v_or_b32_e32 v0, s38, v0
	v_readlane_b32 s40, v254, 50
	v_lshlrev_b32_e32 v0, 8, v0
	v_mov_b32_e32 v1, v209
	v_readlane_b32 s41, v254, 51
	v_lshl_add_u64 v[0:1], s[8:9], 0, v[0:1]
	s_mov_b32 s41, s27
	v_lshl_add_u64 v[0:1], v[0:1], 0, s[40:41]
	v_and_b32_e32 v128, 48, v12
	v_mov_b32_e32 v129, v209
	s_mov_b32 s42, s40
	v_lshl_add_u64 v[84:85], v[0:1], 0, v[128:129]
	v_add_u32_e32 v0, s39, v126
	v_writelane_b32 v254, s42, 50
	v_ashrrev_i32_e32 v1, 31, v0
	v_lshlrev_b64 v[130:131], 8, v[0:1]
	v_writelane_b32 v254, s43, 51
	v_lshl_add_u64 v[2:3], s[8:9], 0, v[130:131]
	v_readlane_b32 s8, v254, 52
	v_readlane_b32 s9, v254, 53
	s_mov_b32 s9, s27
	s_mov_b32 s42, s8
	v_lshl_add_u64 v[26:27], v[2:3], 0, s[8:9]
	s_mov_b32 s8, 0x1a981000
	v_lshlrev_b64 v[122:123], 12, v[0:1]
	v_lshlrev_b64 v[120:121], 6, v[0:1]
	v_add_co_u32_e32 v0, vcc, s8, v64
	s_mov_b32 s8, 0x1a983000
	s_nop 0
	v_addc_co_u32_e32 v1, vcc, 0, v65, vcc
	global_load_dwordx4 v[14:17], v[0:1], off sc1
	v_add_co_u32_e32 v0, vcc, s8, v64
	s_mov_b32 s8, 0x10800000
	s_nop 0
	v_addc_co_u32_e32 v1, vcc, 0, v65, vcc
	global_load_dwordx4 v[18:21], v[0:1], off sc1
	v_add_co_u32_e32 v0, vcc, s8, v66
	s_mov_b32 s8, 0x1a985000
	s_nop 0
	v_addc_co_u32_e32 v1, vcc, 0, v67, vcc
	global_load_dwordx4 v[22:25], v[0:1], off
	v_add_co_u32_e32 v0, vcc, s8, v64
	s_mov_b32 s8, 0x1a987000
	s_nop 0
	v_addc_co_u32_e32 v1, vcc, 0, v65, vcc
	v_add_co_u32_e32 v4, vcc, s8, v64
	s_mov_b32 s8, 0x10840000
	s_nop 0
	v_addc_co_u32_e32 v5, vcc, 0, v65, vcc
	v_add_co_u32_e32 v8, vcc, s8, v66
	s_mov_b32 s8, 0x1a989000
	s_nop 0
	v_addc_co_u32_e32 v9, vcc, 0, v67, vcc
	v_add_co_u32_e32 v28, vcc, s8, v64
	v_readlane_b32 s40, v254, 17
	v_writelane_b32 v254, s42, 52
	v_addc_co_u32_e32 v29, vcc, 0, v65, vcc
	s_mov_b32 s8, 0x1a98b000
	v_lshlrev_b32_e32 v144, 3, v127
	v_mul_lo_u32 v13, v126, s49
	v_writelane_b32 v254, s43, 53
	global_load_dwordx4 v[8:11], v[8:9], off
	v_add_lshl_u32 v146, v13, v144, 1
	global_load_dwordx4 v[36:39], v[28:29], off sc1
	v_add_co_u32_e32 v28, vcc, s8, v64
	s_mov_b32 s8, 0x10880000
	s_nop 0
	v_addc_co_u32_e32 v29, vcc, 0, v65, vcc
	v_readlane_b32 s9, v254, 54
	global_load_dwordx4 v[56:59], v[28:29], off sc1
	v_add_co_u32_e32 v28, vcc, s8, v66
	v_add_u32_e32 v148, s9, v146
	s_nop 0
	v_addc_co_u32_e32 v29, vcc, 0, v67, vcc
	v_mov_b32_e32 v13, v148
	global_load_dwordx4 v[0:3], v[0:1], off sc1
	s_mov_b32 s8, 0x1a98d000
	global_load_dwordx4 v[4:7], v[4:5], off sc1
	s_nop 0
	global_load_dwordx4 v[60:63], v[28:29], off
	global_load_dwordx4 v[112:115], v[84:85], off
	global_load_dwordx4 v[108:111], v[84:85], off offset:64
	global_load_dwordx4 v[104:107], v[84:85], off offset:128
	global_load_dwordx4 v[100:103], v[84:85], off offset:192
	v_or_b32_e32 v32, s40, v144
	s_waitcnt vmcnt(0)
	ds_write_b128 v13, v[14:17]
	ds_write_b128 v13, v[18:21] offset:9216
	ds_write_b128 v13, v[22:25] offset:18432
	v_add_co_u32_e32 v14, vcc, s8, v64
	v_lshlrev_b32_e32 v28, 1, v32
	v_mov_b32_e32 v29, v209
	v_addc_co_u32_e32 v15, vcc, 0, v65, vcc
	s_mov_b32 s8, 0x1a98f000
	v_lshl_add_u64 v[124:125], v[26:27], 0, v[28:29]
	global_load_dwordx4 v[24:27], v[14:15], off sc1
	v_add_co_u32_e32 v14, vcc, s8, v64
	s_mov_b32 s8, 0x108c0000
	s_nop 0
	v_addc_co_u32_e32 v15, vcc, 0, v65, vcc
	s_add_u32 s4, s4, s26
	v_add_lshl_u32 v147, v30, v31, 1
	global_load_dwordx4 v[28:31], v[14:15], off sc1
	v_add_co_u32_e32 v14, vcc, s8, v66
	s_addc_u32 s5, s5, 0
	v_readlane_b32 s8, v254, 48
	s_add_u32 s4, s4, s8
	s_addc_u32 s5, s5, 0
	v_readlane_b32 s8, v254, 49
	s_add_u32 s4, s4, s8
	v_addc_co_u32_e32 v15, vcc, 0, v67, vcc
	s_addc_u32 s5, s5, 0
	v_lshlrev_b32_e32 v135, 5, v127
	global_load_dwordx4 v[32:35], v[14:15], off
	global_load_dwordx4 v[20:23], v135, s[4:5]
	global_load_dwordx4 v[16:19], v135, s[4:5] offset:16
	v_readlane_b32 s4, v254, 18
	s_add_u32 s4, s6, s4
	s_addc_u32 s5, s7, 0
	v_ashrrev_i32_e32 v13, 31, v12
	v_lshl_add_u64 v[14:15], v[12:13], 4, s[4:5]
	s_mov_b32 s4, 0x1b181000
	v_add_co_u32_e32 v40, vcc, s4, v14
	s_mov_b32 s4, 0x1b183000
	s_nop 0
	v_addc_co_u32_e32 v41, vcc, 0, v15, vcc
	v_bfe_u32 v133, v12, 4, 2
	v_lshl_add_u32 v44, v12, 4, 0
	v_add_co_u32_e32 v12, vcc, s4, v14
	global_load_dwordx4 v[40:43], v[40:41], off sc1
	s_nop 0
	v_addc_co_u32_e32 v13, vcc, 0, v15, vcc
	global_load_dwordx4 v[12:15], v[12:13], off sc1
	v_readlane_b32 s5, v254, 55
	s_mov_b32 s4, 0x1a991000
	v_lshlrev_b32_e32 v192, 4, v86
	v_mov_b32_e32 v88, s9
	v_lshlrev_b32_e32 v134, 3, v133
	s_mov_b32 s22, 3
	s_waitcnt vmcnt(1)
	ds_write_b128 v44, v[40:43] offset:8192
	s_waitcnt vmcnt(0)
	ds_write_b128 v44, v[12:15] offset:16384
	v_add_u32_e32 v12, s5, v146
	s_waitcnt lgkmcnt(0)
	s_barrier
	ds_write_b128 v12, v[0:3]
	ds_write_b128 v12, v[4:7] offset:9216
	ds_write_b128 v12, v[8:11] offset:18432
	v_add_co_u32_e32 v0, vcc, s4, v64
	s_mov_b32 s4, 0x1a993000
	s_nop 0
	v_addc_co_u32_e32 v1, vcc, 0, v65, vcc
	global_load_dwordx4 v[44:47], v[0:1], off sc1
	v_add_co_u32_e32 v0, vcc, s4, v64
	s_mov_b32 s4, 0x10900000
	s_nop 0
	v_addc_co_u32_e32 v1, vcc, 0, v65, vcc
	global_load_dwordx4 v[48:51], v[0:1], off sc1
	v_add_co_u32_e32 v0, vcc, s4, v66
	s_mov_b32 s4, 0x1000000
	s_nop 0
	v_addc_co_u32_e32 v1, vcc, 0, v67, vcc
	global_load_dwordx4 v[52:55], v[0:1], off
	v_add_co_u32_e32 v0, vcc, s20, v84
	s_nop 1
	v_addc_co_u32_e32 v1, vcc, 0, v85, vcc
	global_load_dwordx4 v[80:83], v[0:1], off
	global_load_dwordx4 v[76:79], v[0:1], off offset:64
	global_load_dwordx4 v[72:75], v[0:1], off offset:128
	global_load_dwordx4 v[68:71], v[0:1], off offset:192
	v_add_co_u32_e32 v0, vcc, s4, v124
	s_lshl_b32 s4, s23, 2
	s_add_i32 s4, s4, 0
	v_addc_co_u32_e32 v1, vcc, 0, v125, vcc
	v_add_u32_e32 v12, s4, v192
	global_load_dwordx4 v[40:43], v[0:1], off
	ds_read_b128 v[0:3], v12 offset:8192
	ds_read_b128 v[4:7], v12 offset:8224
	ds_read_b128 v[8:11], v12 offset:8256
	ds_read_b128 v[12:15], v12 offset:8288
	s_waitcnt lgkmcnt(3)
	v_pk_mul_f32 v[2:3], v[2:3], 0 op_sel_hi:[1,0]
	v_add_u32_e32 v149, v88, v147
	v_add_u32_e32 v158, v88, v145
	s_waitcnt lgkmcnt(0)
	v_pk_mul_f32 v[14:15], v[14:15], 0 op_sel_hi:[1,0]
	v_pk_mul_f32 v[10:11], v[10:11], 0 op_sel_hi:[1,0]
	v_pk_mul_f32 v[6:7], v[6:7], 0 op_sel_hi:[1,0]
	v_pk_mul_f32 v[12:13], v[12:13], 0 op_sel_hi:[1,0]
	v_pk_mul_f32 v[8:9], v[8:9], 0 op_sel_hi:[1,0]
	v_pk_mul_f32 v[4:5], v[4:5], 0 op_sel_hi:[1,0]
	v_pk_mul_f32 v[0:1], v[0:1], 0 op_sel_hi:[1,0]
	ds_read_b128 v[88:91], v149
	ds_read_b128 v[92:95], v149 offset:32
	ds_read_b128 v[96:99], v158 offset:18432
	ds_read_b128 v[136:139], v158 offset:18464
	ds_read_b128 v[140:143], v149 offset:64
	ds_read_b128 v[150:153], v158 offset:18496
	ds_read_b128 v[154:157], v149 offset:96
	ds_read_b128 v[158:161], v158 offset:18528
	s_waitcnt lgkmcnt(5)
	v_mfma_f32_32x32x16_bf16 v[0:15], v[88:91], v[96:99], v[0:15]
	v_mov_b32_e32 v88, s23
	v_mad_u32_u24 v87, v87, s28, v88
	s_mov_b32 s4, 0x1a995000
	s_addk_i32 s23, 0x80
	s_waitcnt lgkmcnt(4)
	v_mfma_f32_32x32x16_bf16 v[0:15], v[92:95], v[136:139], v[0:15]
	v_lshlrev_b32_e32 v136, 2, v86
	v_or_b32_e32 v86, v87, v136
	s_waitcnt lgkmcnt(2)
	v_mfma_f32_32x32x16_bf16 v[0:15], v[140:143], v[150:153], v[0:15]
	v_lshlrev_b32_e32 v150, 1, v86
	v_add_u32_e32 v151, 0, v150
	v_add_u32_e32 v90, 0x6000, v151
	s_waitcnt lgkmcnt(0)
	v_mfma_f32_32x32x16_bf16 v[0:15], v[154:157], v[158:161], v[0:15]
	s_nop 11
	v_cvt_pk_bf16_f32 v86, v0, v1
	v_cvt_pk_bf16_f32 v87, v2, v3
	v_cvt_pk_bf16_f32 v88, v4, v5
	v_cvt_pk_bf16_f32 v89, v6, v7
	ds_write2_b64 v90, v[86:87], v[88:89] offset1:2
	v_cvt_pk_bf16_f32 v86, v8, v9
	v_cvt_pk_bf16_f32 v87, v10, v11
	v_cvt_pk_bf16_f32 v88, v12, v13
	v_cvt_pk_bf16_f32 v89, v14, v15
	ds_write2_b64 v90, v[86:87], v[88:89] offset0:4 offset1:6
	v_mov_b32_e32 v86, v148
	s_waitcnt lgkmcnt(0)
	s_barrier
	ds_write_b128 v86, v[36:39]
	ds_write_b128 v86, v[56:59] offset:9216
	ds_write_b128 v86, v[60:63] offset:18432
	v_add_co_u32_e32 v36, vcc, s4, v64
	s_mov_b32 s4, 0x1a997000
	s_nop 0
	v_addc_co_u32_e32 v37, vcc, 0, v65, vcc
	global_load_dwordx4 v[56:59], v[36:37], off sc1
	v_add_co_u32_e32 v36, vcc, s4, v64
	s_mov_b32 s4, 0x10940000
	s_nop 0
	v_addc_co_u32_e32 v37, vcc, 0, v65, vcc
	global_load_dwordx4 v[60:63], v[36:37], off sc1
	v_add_co_u32_e32 v36, vcc, s4, v66
	s_mov_b32 s4, 0x8000
	s_nop 0
	v_addc_co_u32_e32 v37, vcc, 0, v67, vcc
	global_load_dwordx4 v[64:67], v[36:37], off
	v_add_co_u32_e32 v36, vcc, s4, v84
	s_mov_b32 s4, 0x1004000
	s_nop 0
	v_addc_co_u32_e32 v37, vcc, 0, v85, vcc
	global_load_dwordx4 v[92:95], v[36:37], off
	global_load_dwordx4 v[96:99], v[36:37], off offset:64
	global_load_dwordx4 v[88:91], v[36:37], off offset:128
	global_load_dwordx4 v[84:87], v[36:37], off offset:192
	v_add_co_u32_e32 v36, vcc, s4, v124
	v_or_b32_e32 v124, s23, v136
	s_nop 0
	v_addc_co_u32_e32 v37, vcc, 0, v125, vcc
	global_load_dwordx4 v[36:39], v[36:37], off
	v_lshl_add_u32 v124, v124, 2, 0
	ds_read_b128 v[136:139], v124 offset:8192
	ds_read_b128 v[140:143], v124 offset:8224
	ds_read_b128 v[152:155], v124 offset:8256
	ds_read_b128 v[156:159], v124 offset:8288
	v_mov_b32_e32 v124, s5
	s_waitcnt lgkmcnt(2)
	v_pk_mul_f32 v[4:5], v[4:5], v[140:141]
	v_add_u32_e32 v125, v124, v147
	s_waitcnt lgkmcnt(0)
	v_pk_mul_f32 v[12:13], v[12:13], v[156:157]
	v_pk_mul_f32 v[8:9], v[8:9], v[152:153]
	v_pk_mul_f32 v[14:15], v[14:15], v[158:159]
	v_pk_mul_f32 v[10:11], v[10:11], v[154:155]
	v_pk_mul_f32 v[6:7], v[6:7], v[142:143]
	v_pk_mul_f32 v[2:3], v[2:3], v[138:139]
	v_pk_mul_f32 v[0:1], v[0:1], v[136:137]
	v_add_u32_e32 v124, v124, v145
	ds_read_b128 v[160:163], v125
	ds_read_b128 v[164:167], v125 offset:32
	ds_read_b128 v[168:171], v124 offset:18432
	ds_read_b128 v[172:175], v124 offset:18464
	ds_read_b128 v[176:179], v125 offset:64
	ds_read_b128 v[180:183], v124 offset:18496
	ds_read_b128 v[184:187], v125 offset:96
	ds_read_b128 v[188:191], v124 offset:18528
	s_waitcnt lgkmcnt(5)
	v_mfma_f32_32x32x16_bf16 v[0:15], v[160:163], v[168:171], v[0:15]
	v_add_u32_e32 v138, 0xa400, v151
	s_ashr_i32 s4, s31, 3
	s_andn2_b32 s4, s4, 31
	s_waitcnt lgkmcnt(4)
	v_mfma_f32_32x32x16_bf16 v[0:15], v[164:167], v[172:175], v[0:15]
	s_waitcnt lgkmcnt(2)
	v_mfma_f32_32x32x16_bf16 v[0:15], v[176:179], v[180:183], v[0:15]
	s_waitcnt lgkmcnt(0)
	v_mfma_f32_32x32x16_bf16 v[0:15], v[184:187], v[188:191], v[0:15]
	s_nop 11
	v_cvt_pk_bf16_f32 v124, v0, v1
	v_cvt_pk_bf16_f32 v125, v2, v3
	v_cvt_pk_bf16_f32 v136, v4, v5
	v_cvt_pk_bf16_f32 v137, v6, v7
	ds_write2_b64 v138, v[124:125], v[136:137] offset1:2
	v_cvt_pk_bf16_f32 v124, v8, v9
	v_cvt_pk_bf16_f32 v125, v10, v11
	v_cvt_pk_bf16_f32 v136, v12, v13
	v_cvt_pk_bf16_f32 v137, v14, v15
	ds_write2_b64 v138, v[124:125], v[136:137] offset0:4 offset1:6
	v_or_b32_e32 v124, s4, v132
	v_mul_lo_u32 v124, v124, s28
	v_add_lshl_u32 v155, v124, v134, 1
	v_add_u32_e32 v152, 0, v155
	v_add_u32_e32 v124, 0x6000, v152
	ds_read_b128 v[136:139], v124
	ds_read_b128 v[140:143], v124 offset:4352
	ds_read_b128 v[156:159], v124 offset:64
	ds_read_b128 v[160:163], v124 offset:4416
	ds_read_b128 v[164:167], v124 offset:128
	ds_read_b128 v[168:171], v124 offset:4480
	ds_read_b128 v[172:175], v124 offset:192
	ds_read_b128 v[176:179], v124 offset:4544
	s_waitcnt lgkmcnt(7)
	v_mfma_f32_16x16x32_bf16 v[136:139], v[112:115], v[136:139], 0
	v_lshl_or_b32 v124, v133, 2, s38
	s_lshl_b32 s26, s4, 2
	s_add_i32 s23, s26, 0
	s_waitcnt lgkmcnt(6)
	v_mfma_f32_16x16x32_bf16 v[112:115], v[112:115], v[140:143], 0
	v_lshlrev_b32_e32 v154, 2, v132
	v_readlane_b32 s8, v254, 35
	v_readlane_b32 s9, v254, 36
	s_waitcnt lgkmcnt(5)
	v_mfma_f32_16x16x32_bf16 v[136:139], v[108:111], v[156:159], v[136:139]
	v_mul_u32_u24_e32 v156, 0x41, v124
	v_lshlrev_b32_e32 v153, 2, v156
	v_add3_u32 v157, s23, v153, v154
	s_waitcnt lgkmcnt(4)
	v_mfma_f32_16x16x32_bf16 v[108:111], v[108:111], v[160:163], v[112:115]
	v_add_u32_e32 v124, 0xe800, v157
	v_lshl_add_u32 v159, v126, 6, v126
	s_waitcnt lgkmcnt(3)
	v_mfma_f32_16x16x32_bf16 v[112:115], v[104:107], v[164:167], v[136:139]
	v_cmp_eq_u32_e64 s[4:5], 0, v127
	v_lshlrev_b32_e32 v149, 2, v159
	v_add3_u32 v160, 0, v149, v135
	s_waitcnt lgkmcnt(2)
	v_mfma_f32_16x16x32_bf16 v[104:107], v[104:107], v[168:171], v[108:111]
	s_waitcnt lgkmcnt(1)
	v_mfma_f32_16x16x32_bf16 v[112:115], v[100:103], v[172:175], v[112:115]
	s_waitcnt lgkmcnt(0)
	v_mfma_f32_16x16x32_bf16 v[100:103], v[100:103], v[176:179], v[104:107]
	s_nop 5
	v_mul_f32_e32 v112, 0x3db504f3, v112
	s_nop 0
	v_mul_f32_e32 v100, 0x3db504f3, v100
	v_mul_f32_e32 v108, 0x3db504f3, v113
	ds_write2_b32 v124, v112, v100 offset1:16
	v_mul_f32_e32 v100, 0x3db504f3, v101
	v_mul_f32_e32 v109, 0x3db504f3, v114
	ds_write2_b32 v124, v108, v100 offset0:65 offset1:81
	v_mul_f32_e32 v100, 0x3db504f3, v102
	v_mul_f32_e32 v110, 0x3db504f3, v115
	ds_write2_b32 v124, v109, v100 offset0:130 offset1:146
	v_mul_f32_e32 v100, 0x3db504f3, v103
	ds_write2_b32 v124, v110, v100 offset0:195 offset1:211
	v_lshl_add_u64 v[100:101], s[8:9], 0, v[208:209]
	v_readlane_b32 s8, v254, 38
	v_readlane_b32 s9, v254, 39
	v_lshl_add_u64 v[124:125], v[100:101], 0, v[116:117]
	s_waitcnt lgkmcnt(0)
	s_barrier
	v_lshl_add_u64 v[100:101], s[8:9], 0, v[118:119]
	s_add_i32 s8, s39, s38
	v_lshl_add_u64 v[126:127], v[100:101], 0, v[208:209]
	v_add_lshl_u32 v100, s8, v132, 8
	v_readlane_b32 s8, v254, 40
	v_mov_b32_e32 v101, v209
	v_readlane_b32 s9, v254, 41
	v_add_lshl_u32 v102, s40, v144, 1
	v_mov_b32_e32 v103, v209
	v_lshl_add_u64 v[100:101], s[8:9], 0, v[100:101]
	s_and_b32 s8, s31, 0xffffff80
	s_add_i32 s8, s8, 0
	s_addk_i32 s8, 0x2400
	v_add_u32_e32 v161, s8, v192
	v_readlane_b32 s8, v254, 42
	v_readlane_b32 s9, v254, 43
	v_lshl_add_u64 v[128:129], v[100:101], 0, v[128:129]
	s_nop 0
	v_lshl_add_u64 v[100:101], s[8:9], 0, v[130:131]
	v_readlane_b32 s8, v254, 44
	v_lshl_add_u64 v[130:131], v[100:101], 0, v[102:103]
	s_nop 0
	v_or_b32_e32 v122, s8, v122
	v_readlane_b32 s8, v254, 45
	v_lshl_add_u64 v[122:123], v[122:123], 0, v[208:209]
	s_nop 0
	v_or_b32_e32 v120, s8, v120
	s_branch .LBB0_1086

.LBB0_1086:
	s_and_b32 s40, s22, 1
	s_mul_i32 s8, s40, 0x6c00
	v_readlane_b32 s38, v254, 54
	s_add_i32 s41, s38, s8
	v_add_u32_e32 v100, s41, v146
	v_lshl_add_u64 v[132:133], s[6:7], 0, v[124:125]
	ds_write_b128 v100, v[24:27]
	ds_write_b128 v100, v[28:31] offset:9216
	ds_write_b128 v100, v[32:35] offset:18432
	v_add_co_u32_e32 v28, vcc, s17, v132
	v_lshl_add_u64 v[136:137], s[6:7], 0, v[128:129]
	s_nop 0
	v_addc_co_u32_e32 v29, vcc, 0, v133, vcc
	s_mov_b32 s8, 0xb40c000
	v_add_co_u32_e32 v32, vcc, s8, v136
	v_lshl_add_u64 v[138:139], s[6:7], 0, v[126:127]
	s_nop 0
	v_addc_co_u32_e32 v33, vcc, 0, v137, vcc
	v_lshl_add_u64 v[140:141], s[6:7], 0, v[130:131]
	global_load_dwordx4 v[24:27], v[132:133], off sc1
	s_nop 0
	global_load_dwordx4 v[28:31], v[28:29], off sc1
	s_nop 0
	global_load_dwordx4 v[116:119], v[32:33], off
	global_load_dwordx4 v[112:115], v[32:33], off offset:64
	global_load_dwordx4 v[108:111], v[32:33], off offset:128
	global_load_dwordx4 v[104:107], v[32:33], off offset:192
	s_nop 0
	global_load_dwordx4 v[32:35], v[138:139], off
	global_load_dwordx4 v[100:103], v[140:141], off
	s_add_i32 s31, s22, -1
	s_and_b32 s8, s31, 1
	s_mul_i32 s9, s8, 0x6c00
	s_add_i32 s38, s38, s9
	v_mov_b32_e32 v134, s38
	ds_read_b128 v[162:165], v161
	ds_read_b128 v[166:169], v161 offset:32
	ds_read_b128 v[170:173], v161 offset:64
	ds_read_b128 v[174:177], v161 offset:96
	s_waitcnt lgkmcnt(3)
	v_pk_mul_f32 v[2:3], v[2:3], v[164:165]
	v_add_u32_e32 v135, v134, v147
	v_add_u32_e32 v134, v134, v145
	ds_read_b128 v[178:181], v135
	ds_read_b128 v[182:185], v134 offset:18432
	s_waitcnt lgkmcnt(2)
	v_pk_mul_f32 v[14:15], v[14:15], v[176:177]
	v_pk_mul_f32 v[10:11], v[10:11], v[172:173]
	v_pk_mul_f32 v[6:7], v[6:7], v[168:169]
	v_pk_mul_f32 v[12:13], v[12:13], v[174:175]
	v_pk_mul_f32 v[8:9], v[8:9], v[170:171]
	v_pk_mul_f32 v[4:5], v[4:5], v[166:167]
	v_pk_mul_f32 v[0:1], v[0:1], v[162:163]
	ds_read_b128 v[162:165], v135 offset:32
	ds_read_b128 v[166:169], v134 offset:18464
	s_waitcnt lgkmcnt(2)
	v_mfma_f32_32x32x16_bf16 v[0:15], v[178:181], v[182:185], v[0:15]
	s_mul_i32 s9, s8, 0x4400
	s_add_i32 s42, s9, 0
	s_xor_b32 s39, s8, 1
	s_mul_i32 s9, s39, 0x4400
	s_waitcnt lgkmcnt(0)
	v_mfma_f32_32x32x16_bf16 v[0:15], v[162:165], v[166:169], v[0:15]
	ds_read_b128 v[162:165], v135 offset:64
	ds_read_b128 v[166:169], v134 offset:18496
	ds_read_b128 v[170:173], v135 offset:96
	ds_read_b128 v[174:177], v134 offset:18528
	v_add_u32_e32 v134, s42, v150
	s_waitcnt lgkmcnt(2)
	v_mfma_f32_32x32x16_bf16 v[0:15], v[162:165], v[166:169], v[0:15]
	v_add_u32_e32 v162, 0x6000, v134
	v_mov_b32_e32 v158, v162
	s_waitcnt lgkmcnt(0)
	v_mfma_f32_32x32x16_bf16 v[0:15], v[170:173], v[174:177], v[0:15]
	s_nop 11
	v_cvt_pk_bf16_f32 v134, v0, v1
	v_cvt_pk_bf16_f32 v135, v2, v3
	v_cvt_pk_bf16_f32 v142, v4, v5
	v_cvt_pk_bf16_f32 v143, v6, v7
	ds_write2_b64 v158, v[134:135], v[142:143] offset1:2
	v_cvt_pk_bf16_f32 v134, v8, v9
	v_cvt_pk_bf16_f32 v135, v10, v11
	v_cvt_pk_bf16_f32 v142, v12, v13
	v_cvt_pk_bf16_f32 v143, v14, v15
	ds_write2_b64 v158, v[134:135], v[142:143] offset0:4 offset1:6
	v_add_u32_e32 v134, s9, v152
	v_add_u32_e32 v164, 0x6000, v134
	v_mov_b32_e32 v134, v164
	ds_read_b128 v[166:169], v134
	ds_read_b128 v[170:173], v134 offset:64
	ds_read_b128 v[174:177], v134 offset:4352
	ds_read_b128 v[178:181], v134 offset:4416
	ds_read_b128 v[182:185], v134 offset:128
	ds_read_b128 v[186:189], v134 offset:192
	ds_read_b128 v[190:193], v134 offset:4480
	ds_read_b128 v[194:197], v134 offset:4544
	v_lshl_add_u64 v[134:135], s[6:7], 0, v[120:121]
	s_waitcnt vmcnt(20) lgkmcnt(7)
	v_mfma_f32_16x16x32_bf16 v[166:169], v[80:83], v[166:169], 0
	s_mul_i32 s9, s39, 0x4100
	v_add_u32_e32 v142, s9, v157
	v_add_u32_e32 v163, 0xe800, v142
	s_waitcnt lgkmcnt(5)
	v_mfma_f32_16x16x32_bf16 v[80:83], v[80:83], v[174:177], 0
	v_mov_b32_e32 v142, v163
	s_mulk_i32 s8, 0xfd00
	s_waitcnt vmcnt(19)
	v_mfma_f32_16x16x32_bf16 v[166:169], v[76:79], v[170:173], v[166:169]
	s_add_i32 s43, s42, s8
	v_lshlrev_b32_e32 v158, 2, v144
	s_mov_b32 s8, 0xe800
	s_waitcnt lgkmcnt(4)
	v_mfma_f32_16x16x32_bf16 v[76:79], v[76:79], v[178:181], v[80:83]
	s_waitcnt vmcnt(18) lgkmcnt(3)
	v_mfma_f32_16x16x32_bf16 v[80:83], v[72:75], v[182:185], v[166:169]
	s_waitcnt lgkmcnt(1)
	v_mfma_f32_16x16x32_bf16 v[72:75], v[72:75], v[190:193], v[76:79]
	s_waitcnt vmcnt(17)
	v_mfma_f32_16x16x32_bf16 v[80:83], v[68:71], v[186:189], v[80:83]
	s_waitcnt lgkmcnt(0)
	v_mfma_f32_16x16x32_bf16 v[68:71], v[68:71], v[194:197], v[72:75]
	s_nop 5
	v_mul_f32_e32 v80, 0x3db504f3, v80
	s_nop 0
	v_mul_f32_e32 v68, 0x3db504f3, v68
	v_mul_f32_e32 v76, 0x3db504f3, v81
	ds_write2_b32 v142, v80, v68 offset1:16
	v_mul_f32_e32 v68, 0x3db504f3, v69
	v_mul_f32_e32 v77, 0x3db504f3, v82
	ds_write2_b32 v142, v76, v68 offset0:65 offset1:81
	v_mul_f32_e32 v68, 0x3db504f3, v70
	v_mul_f32_e32 v78, 0x3db504f3, v83
	ds_write2_b32 v142, v77, v68 offset0:130 offset1:146
	v_mul_f32_e32 v68, 0x3db504f3, v71
	ds_write2_b32 v142, v78, v68 offset0:195 offset1:211
	v_lshl_add_u32 v68, v159, 2, s43
	v_add3_u32 v165, v68, v158, s8
	v_mov_b32_e32 v68, v165
	ds_read2_b32 v[74:75], v68 offset1:1
	ds_read2_b32 v[72:73], v68 offset0:2 offset1:3
	ds_read2_b32 v[70:71], v68 offset0:4 offset1:5
	ds_read2_b32 v[68:69], v68 offset0:6 offset1:7
	s_waitcnt lgkmcnt(3)
	v_pk_mul_f32 v[76:77], v[74:75], v[74:75]
	s_waitcnt lgkmcnt(2)
	v_pk_mul_f32 v[78:79], v[72:73], v[72:73]
	v_add_f32_e32 v76, v76, v77
	v_add_f32_e32 v76, v76, v78
	s_waitcnt lgkmcnt(1)
	v_pk_mul_f32 v[80:81], v[70:71], v[70:71]
	v_add_f32_e32 v76, v76, v79
	v_add_f32_e32 v76, v76, v80
	s_waitcnt lgkmcnt(0)
	v_pk_mul_f32 v[82:83], v[68:69], v[68:69]
	v_add_f32_e32 v76, v76, v81
	v_add_f32_e32 v76, v76, v82
	v_add_f32_e32 v76, v76, v83
	s_nop 1
	v_add_f32_dpp v76, v76, v76 quad_perm:[1,0,3,2] row_mask:0xf bank_mask:0xf bound_ctrl:1
	s_nop 1
	v_add_f32_dpp v76, v76, v76 quad_perm:[2,3,0,1] row_mask:0xf bank_mask:0xf bound_ctrl:1
	s_nop 1
	v_mov_b32_dpp v77, v76 row_half_mirror row_mask:0xf bank_mask:0xf bound_ctrl:1
	s_and_saveexec_b64 s[8:9], s[4:5]
	s_cbranch_execz .LBB0_1088
	v_add_f32_e32 v78, v76, v77
	v_add_co_u32_e32 v76, vcc, 0x1a900000, v134
	s_nop 1
	v_addc_co_u32_e32 v77, vcc, 0, v135, vcc
	global_store_dword v[76:77], v78, off
.LBB0_1088:
	s_or_b64 exec, exec, s[8:9]
	s_waitcnt vmcnt(16)
	v_lshlrev_b32_e32 v76, 16, v40
	v_and_b32_e32 v77, 0xffff0000, v40
	v_mul_f32_e32 v40, 0xbfb8aa3b, v76
	v_exp_f32_e32 v40, v40
	v_pk_mul_f32 v[74:75], v[20:21], v[74:75]
	v_pk_mul_f32 v[72:73], v[22:23], v[72:73]
	v_pk_mul_f32 v[70:71], v[16:17], v[70:71]
	v_add_f32_e32 v40, 1.0, v40
	v_rcp_f32_e32 v78, v40
	v_mul_f32_e32 v40, 0xbfb8aa3b, v77
	v_exp_f32_e32 v40, v40
	s_mov_b64 s[8:9], 0x2000
	v_pk_mul_f32 v[68:69], v[18:19], v[68:69]
	v_lshl_add_u64 v[142:143], v[132:133], 0, s[8:9]
	v_add_f32_e32 v40, 1.0, v40
	v_rcp_f32_e32 v79, v40
	v_lshl_add_u64 v[132:133], s[6:7], 0, v[122:123]
	s_mov_b32 s8, 0x12800000
	s_bitcmp1_b32 s31, 0
	v_pk_mul_f32 v[76:77], v[78:79], v[76:77]
	s_nop 0
	v_pk_mul_f32 v[74:75], v[76:77], v[74:75]
	s_nop 0
	v_cvt_pk_bf16_f32 v40, v74, v75
	v_lshlrev_b32_e32 v74, 16, v41
	v_and_b32_e32 v75, 0xffff0000, v41
	v_mul_f32_e32 v41, 0xbfb8aa3b, v74
	v_exp_f32_e32 v41, v41
	s_nop 0
	v_add_f32_e32 v41, 1.0, v41
	v_rcp_f32_e32 v76, v41
	v_mul_f32_e32 v41, 0xbfb8aa3b, v75
	v_exp_f32_e32 v41, v41
	s_nop 0
	v_add_f32_e32 v41, 1.0, v41
	v_rcp_f32_e32 v77, v41
	s_nop 0
	v_pk_mul_f32 v[74:75], v[76:77], v[74:75]
	s_nop 0
	v_pk_mul_f32 v[72:73], v[74:75], v[72:73]
	s_nop 0
	v_cvt_pk_bf16_f32 v41, v72, v73
	v_lshlrev_b32_e32 v72, 16, v42
	v_and_b32_e32 v73, 0xffff0000, v42
	v_mul_f32_e32 v42, 0xbfb8aa3b, v72
	v_exp_f32_e32 v42, v42
	s_nop 0
	v_add_f32_e32 v42, 1.0, v42
	v_rcp_f32_e32 v74, v42
	v_mul_f32_e32 v42, 0xbfb8aa3b, v73
	v_exp_f32_e32 v42, v42
	s_nop 0
	v_add_f32_e32 v42, 1.0, v42
	v_rcp_f32_e32 v75, v42
	s_nop 0
	v_pk_mul_f32 v[72:73], v[74:75], v[72:73]
	s_nop 0
	v_pk_mul_f32 v[70:71], v[72:73], v[70:71]
	s_nop 0
	v_cvt_pk_bf16_f32 v42, v70, v71
	v_lshlrev_b32_e32 v70, 16, v43
	v_and_b32_e32 v71, 0xffff0000, v43
	v_mul_f32_e32 v43, 0xbfb8aa3b, v70
	v_exp_f32_e32 v43, v43
	s_nop 0
	v_add_f32_e32 v43, 1.0, v43
	v_rcp_f32_e32 v72, v43
	v_mul_f32_e32 v43, 0xbfb8aa3b, v71
	v_exp_f32_e32 v43, v43
	s_nop 0
	v_add_f32_e32 v43, 1.0, v43
	v_rcp_f32_e32 v73, v43
	s_nop 0
	v_pk_mul_f32 v[70:71], v[72:73], v[70:71]
	s_nop 0
	v_pk_mul_f32 v[68:69], v[70:71], v[68:69]
	s_nop 0
	v_cvt_pk_bf16_f32 v43, v68, v69
	v_add_co_u32_e32 v68, vcc, s8, v132
	s_cselect_b32 s8, 0x6c00, 0
	s_nop 0
	v_addc_co_u32_e32 v69, vcc, 0, v133, vcc
	global_store_dwordx4 v[68:69], v[40:43], off
	s_waitcnt lgkmcnt(0)
	s_barrier
	s_nop 0
	v_add_u32_e32 v40, s8, v148
	ds_write_b128 v40, v[44:47]
	ds_write_b128 v40, v[48:51] offset:9216
	ds_write_b128 v40, v[52:55] offset:18432
	v_add_co_u32_e32 v40, vcc, s17, v142
	s_mov_b32 s8, 0x40000
	s_nop 0
	v_addc_co_u32_e32 v41, vcc, 0, v143, vcc
	global_load_dwordx4 v[44:47], v[40:41], off sc1
	v_add_co_u32_e32 v40, vcc, s20, v142
	s_nop 1
	v_addc_co_u32_e32 v41, vcc, 0, v143, vcc
	global_load_dwordx4 v[48:51], v[40:41], off sc1
	v_add_co_u32_e32 v40, vcc, s8, v138
	s_mov_b32 s8, 0xb410000
	s_nop 0
	v_addc_co_u32_e32 v41, vcc, 0, v139, vcc
	global_load_dwordx4 v[52:55], v[40:41], off
	v_add_co_u32_e32 v40, vcc, s8, v136
	s_mul_i32 s8, s40, 0x4400
	s_nop 0
	v_addc_co_u32_e32 v41, vcc, 0, v137, vcc
	global_load_dwordx4 v[80:83], v[40:41], off
	global_load_dwordx4 v[76:79], v[40:41], off offset:64
	global_load_dwordx4 v[72:75], v[40:41], off offset:128
	global_load_dwordx4 v[68:71], v[40:41], off offset:192
	v_add_co_u32_e32 v40, vcc, s20, v140
	s_nop 1
	v_addc_co_u32_e32 v41, vcc, 0, v141, vcc
	global_load_dwordx4 v[40:43], v[40:41], off
	ds_read_b128 v[166:169], v161 offset:512
	ds_read_b128 v[170:173], v161 offset:544
	ds_read_b128 v[174:177], v161 offset:576
	ds_read_b128 v[178:181], v161 offset:608
	s_waitcnt lgkmcnt(3)
	v_pk_mul_f32 v[0:1], v[0:1], v[166:167]
	v_mov_b32_e32 v166, s41
	s_waitcnt lgkmcnt(1)
	v_pk_mul_f32 v[10:11], v[10:11], v[176:177]
	s_waitcnt lgkmcnt(0)
	v_pk_mul_f32 v[14:15], v[14:15], v[180:181]
	v_pk_mul_f32 v[6:7], v[6:7], v[172:173]
	v_pk_mul_f32 v[2:3], v[2:3], v[168:169]
	v_pk_mul_f32 v[12:13], v[12:13], v[178:179]
	v_pk_mul_f32 v[8:9], v[8:9], v[174:175]
	v_pk_mul_f32 v[4:5], v[4:5], v[170:171]
	s_nop 0
	v_add_u32_e32 v190, v166, v147
	v_add_u32_e32 v194, v166, v145
	ds_read_b128 v[166:169], v190
	ds_read_b128 v[170:173], v190 offset:32
	ds_read_b128 v[174:177], v194 offset:18432
	ds_read_b128 v[178:181], v194 offset:18464
	ds_read_b128 v[182:185], v190 offset:64
	ds_read_b128 v[186:189], v194 offset:18496
	ds_read_b128 v[190:193], v190 offset:96
	ds_read_b128 v[194:197], v194 offset:18528
	s_waitcnt lgkmcnt(5)
	v_mfma_f32_32x32x16_bf16 v[0:15], v[166:169], v[174:177], v[0:15]
	v_add_u32_e32 v166, s8, v151
	s_waitcnt lgkmcnt(4)
	v_mfma_f32_32x32x16_bf16 v[0:15], v[170:173], v[178:181], v[0:15]
	v_add_u32_e32 v170, 0x6000, v166
	s_waitcnt lgkmcnt(2)
	v_mfma_f32_32x32x16_bf16 v[0:15], v[182:185], v[186:189], v[0:15]
	s_waitcnt lgkmcnt(0)
	v_mfma_f32_32x32x16_bf16 v[0:15], v[190:193], v[194:197], v[0:15]
	s_nop 11
	v_cvt_pk_bf16_f32 v166, v0, v1
	v_cvt_pk_bf16_f32 v167, v2, v3
	v_cvt_pk_bf16_f32 v168, v4, v5
	v_cvt_pk_bf16_f32 v169, v6, v7
	ds_write2_b64 v170, v[166:167], v[168:169] offset1:2
	v_cvt_pk_bf16_f32 v166, v8, v9
	v_cvt_pk_bf16_f32 v167, v10, v11
	v_cvt_pk_bf16_f32 v168, v12, v13
	v_cvt_pk_bf16_f32 v169, v14, v15
	ds_write2_b64 v170, v[166:167], v[168:169] offset0:4 offset1:6
	v_add_u32_e32 v166, s42, v155
	v_add_u32_e32 v194, 0x6000, v166
	ds_read_b128 v[166:169], v194
	ds_read_b128 v[170:173], v194 offset:4352
	ds_read_b128 v[174:177], v194 offset:64
	ds_read_b128 v[178:181], v194 offset:4416
	ds_read_b128 v[182:185], v194 offset:128
	ds_read_b128 v[186:189], v194 offset:4480
	ds_read_b128 v[190:193], v194 offset:192
	ds_read_b128 v[194:197], v194 offset:4544
	s_waitcnt vmcnt(21) lgkmcnt(7)
	v_mfma_f32_16x16x32_bf16 v[166:169], v[92:95], v[166:169], 0
	s_add_i32 s8, s26, s43
	s_mulk_i32 s40, 0x4100
	s_waitcnt lgkmcnt(6)
	v_mfma_f32_16x16x32_bf16 v[92:95], v[92:95], v[170:173], 0
	s_waitcnt vmcnt(20) lgkmcnt(5)
	v_mfma_f32_16x16x32_bf16 v[166:169], v[96:99], v[174:177], v[166:169]
	s_waitcnt lgkmcnt(4)
	v_mfma_f32_16x16x32_bf16 v[92:95], v[96:99], v[178:181], v[92:95]
	s_waitcnt vmcnt(19) lgkmcnt(3)
	v_mfma_f32_16x16x32_bf16 v[96:99], v[88:91], v[182:185], v[166:169]
	s_waitcnt lgkmcnt(2)
	v_mfma_f32_16x16x32_bf16 v[88:91], v[88:91], v[186:189], v[92:95]
	s_nop 1
	v_lshl_add_u32 v166, v156, 2, s8
	s_mov_b32 s8, 0xe800
	v_add3_u32 v166, v166, v154, s8
	s_waitcnt vmcnt(18) lgkmcnt(1)
	v_mfma_f32_16x16x32_bf16 v[96:99], v[84:87], v[190:193], v[96:99]
	s_waitcnt lgkmcnt(0)
	v_mfma_f32_16x16x32_bf16 v[84:87], v[84:87], v[194:197], v[88:91]
	s_nop 5
	v_mul_f32_e32 v96, 0x3db504f3, v96
	s_nop 0
	v_mul_f32_e32 v84, 0x3db504f3, v84
	v_mul_f32_e32 v92, 0x3db504f3, v97
	ds_write2_b32 v166, v96, v84 offset1:16
	v_mul_f32_e32 v84, 0x3db504f3, v85
	v_mul_f32_e32 v93, 0x3db504f3, v98
	ds_write2_b32 v166, v92, v84 offset0:65 offset1:81
	v_mul_f32_e32 v84, 0x3db504f3, v86
	v_mul_f32_e32 v94, 0x3db504f3, v99
	ds_write2_b32 v166, v93, v84 offset0:130 offset1:146
	v_mul_f32_e32 v84, 0x3db504f3, v87
	ds_write2_b32 v166, v94, v84 offset0:195 offset1:211
	v_add_u32_e32 v84, s40, v160
	v_add_u32_e32 v84, 0xe800, v84
	ds_read2_b32 v[92:93], v84 offset1:1
	ds_read2_b32 v[90:91], v84 offset0:2 offset1:3
	ds_read2_b32 v[88:89], v84 offset0:4 offset1:5
	ds_read2_b32 v[86:87], v84 offset0:6 offset1:7
	s_waitcnt lgkmcnt(3)
	v_pk_mul_f32 v[84:85], v[92:93], v[92:93]
	s_waitcnt lgkmcnt(2)
	v_pk_mul_f32 v[94:95], v[90:91], v[90:91]
	v_add_f32_e32 v84, v84, v85
	v_add_f32_e32 v84, v84, v94
	s_waitcnt lgkmcnt(1)
	v_pk_mul_f32 v[96:97], v[88:89], v[88:89]
	v_add_f32_e32 v84, v84, v95
	v_add_f32_e32 v84, v84, v96
	s_waitcnt lgkmcnt(0)
	v_pk_mul_f32 v[98:99], v[86:87], v[86:87]
	v_add_f32_e32 v84, v84, v97
	v_add_f32_e32 v84, v84, v98
	v_add_f32_e32 v84, v84, v99
	s_nop 1
	v_add_f32_dpp v84, v84, v84 quad_perm:[1,0,3,2] row_mask:0xf bank_mask:0xf bound_ctrl:1
	s_nop 1
	v_add_f32_dpp v84, v84, v84 quad_perm:[2,3,0,1] row_mask:0xf bank_mask:0xf bound_ctrl:1
	s_nop 1
	v_mov_b32_dpp v85, v84 row_half_mirror row_mask:0xf bank_mask:0xf bound_ctrl:1
	s_and_saveexec_b64 s[8:9], s[4:5]
	s_cbranch_execz .LBB0_1090
	v_add_f32_e32 v94, v84, v85
	v_add_co_u32_e32 v84, vcc, 0x1a901000, v134
	s_nop 1
	v_addc_co_u32_e32 v85, vcc, 0, v135, vcc
	global_store_dword v[84:85], v94, off
.LBB0_1090:
	s_or_b64 exec, exec, s[8:9]
	s_waitcnt vmcnt(17)
	v_lshlrev_b32_e32 v96, 16, v36
	v_and_b32_e32 v97, 0xffff0000, v36
	v_mul_f32_e32 v36, 0xbfb8aa3b, v96
	v_exp_f32_e32 v36, v36
	v_pk_mul_f32 v[92:93], v[20:21], v[92:93]
	v_pk_mul_f32 v[90:91], v[22:23], v[90:91]
	v_pk_mul_f32 v[88:89], v[16:17], v[88:89]
	v_add_f32_e32 v36, 1.0, v36
	v_rcp_f32_e32 v98, v36
	v_mul_f32_e32 v36, 0xbfb8aa3b, v97
	v_exp_f32_e32 v36, v36
	s_mov_b64 s[8:9], 0x40000
	v_pk_mul_f32 v[86:87], v[18:19], v[86:87]
	v_lshl_add_u64 v[84:85], v[138:139], 0, s[8:9]
	v_add_f32_e32 v36, 1.0, v36
	v_rcp_f32_e32 v99, v36
	s_mov_b32 s8, 0x12840000
	s_mulk_i32 s39, 0x6c00
	s_mov_b64 s[40:41], 0x4000
	v_pk_mul_f32 v[96:97], v[98:99], v[96:97]
	v_lshl_add_u64 v[94:95], v[142:143], 0, s[40:41]
	v_pk_mul_f32 v[92:93], v[96:97], v[92:93]
	v_lshl_add_u64 v[138:139], v[140:141], 0, s[40:41]
	v_cvt_pk_bf16_f32 v36, v92, v93
	v_lshlrev_b32_e32 v92, 16, v37
	v_and_b32_e32 v93, 0xffff0000, v37
	v_mul_f32_e32 v37, 0xbfb8aa3b, v92
	v_exp_f32_e32 v37, v37
	s_nop 0
	v_add_f32_e32 v37, 1.0, v37
	v_rcp_f32_e32 v96, v37
	v_mul_f32_e32 v37, 0xbfb8aa3b, v93
	v_exp_f32_e32 v37, v37
	s_nop 0
	v_add_f32_e32 v37, 1.0, v37
	v_rcp_f32_e32 v97, v37
	s_nop 0
	v_pk_mul_f32 v[92:93], v[96:97], v[92:93]
	s_nop 0
	v_pk_mul_f32 v[90:91], v[92:93], v[90:91]
	s_nop 0
	v_cvt_pk_bf16_f32 v37, v90, v91
	v_lshlrev_b32_e32 v90, 16, v38
	v_and_b32_e32 v91, 0xffff0000, v38
	v_mul_f32_e32 v38, 0xbfb8aa3b, v90
	v_exp_f32_e32 v38, v38
	s_nop 0
	v_add_f32_e32 v38, 1.0, v38
	v_rcp_f32_e32 v92, v38
	v_mul_f32_e32 v38, 0xbfb8aa3b, v91
	v_exp_f32_e32 v38, v38
	s_nop 0
	v_add_f32_e32 v38, 1.0, v38
	v_rcp_f32_e32 v93, v38
	s_nop 0
	v_pk_mul_f32 v[90:91], v[92:93], v[90:91]
	s_nop 0
	v_pk_mul_f32 v[88:89], v[90:91], v[88:89]
	s_nop 0
	v_cvt_pk_bf16_f32 v38, v88, v89
	v_lshlrev_b32_e32 v88, 16, v39
	v_and_b32_e32 v89, 0xffff0000, v39
	v_mul_f32_e32 v39, 0xbfb8aa3b, v88
	v_exp_f32_e32 v39, v39
	s_nop 0
	v_add_f32_e32 v39, 1.0, v39
	v_rcp_f32_e32 v90, v39
	v_mul_f32_e32 v39, 0xbfb8aa3b, v89
	v_exp_f32_e32 v39, v39
	s_nop 0
	v_add_f32_e32 v39, 1.0, v39
	v_rcp_f32_e32 v91, v39
	s_nop 0
	v_pk_mul_f32 v[88:89], v[90:91], v[88:89]
	s_nop 0
	v_pk_mul_f32 v[86:87], v[88:89], v[86:87]
	s_nop 0
	v_cvt_pk_bf16_f32 v39, v86, v87
	v_add_co_u32_e32 v86, vcc, s8, v132
	s_mov_b32 s8, 0x40000
	s_nop 0
	v_addc_co_u32_e32 v87, vcc, 0, v133, vcc
	global_store_dwordx4 v[86:87], v[36:39], off
	s_waitcnt lgkmcnt(0)
	s_barrier
	s_nop 0
	v_add_u32_e32 v36, s39, v148
	ds_write_b128 v36, v[56:59]
	ds_write_b128 v36, v[60:63] offset:9216
	ds_write_b128 v36, v[64:67] offset:18432
	v_add_co_u32_e32 v36, vcc, s17, v94
	s_nop 1
	v_addc_co_u32_e32 v37, vcc, 0, v95, vcc
	global_load_dwordx4 v[56:59], v[36:37], off sc1
	v_add_co_u32_e32 v36, vcc, s20, v94
	s_nop 1
	v_addc_co_u32_e32 v37, vcc, 0, v95, vcc
	global_load_dwordx4 v[60:63], v[36:37], off sc1
	v_add_co_u32_e32 v36, vcc, s8, v84
	s_mov_b32 s8, 0xb414000
	s_nop 0
	v_addc_co_u32_e32 v37, vcc, 0, v85, vcc
	global_load_dwordx4 v[64:67], v[36:37], off
	v_add_co_u32_e32 v36, vcc, s8, v136
	s_nop 1
	v_addc_co_u32_e32 v37, vcc, 0, v137, vcc
	global_load_dwordx4 v[92:95], v[36:37], off
	global_load_dwordx4 v[96:99], v[36:37], off offset:64
	global_load_dwordx4 v[88:91], v[36:37], off offset:128
	global_load_dwordx4 v[84:87], v[36:37], off offset:192
	v_add_co_u32_e32 v36, vcc, s20, v138
	s_nop 1
	v_addc_co_u32_e32 v37, vcc, 0, v139, vcc
	global_load_dwordx4 v[36:39], v[36:37], off
	ds_read_b128 v[136:139], v161 offset:1024
	ds_read_b128 v[140:143], v161 offset:1056
	ds_read_b128 v[166:169], v161 offset:1088
	ds_read_b128 v[170:173], v161 offset:1120
	s_waitcnt lgkmcnt(3)
	v_pk_mul_f32 v[0:1], v[0:1], v[136:137]
	v_mov_b32_e32 v136, s38
	s_waitcnt lgkmcnt(1)
	v_pk_mul_f32 v[10:11], v[10:11], v[168:169]
	s_waitcnt lgkmcnt(0)
	v_pk_mul_f32 v[14:15], v[14:15], v[172:173]
	v_pk_mul_f32 v[6:7], v[6:7], v[142:143]
	v_pk_mul_f32 v[2:3], v[2:3], v[138:139]
	v_pk_mul_f32 v[12:13], v[12:13], v[170:171]
	v_pk_mul_f32 v[8:9], v[8:9], v[166:167]
	v_pk_mul_f32 v[4:5], v[4:5], v[140:141]
	s_nop 0
	v_add_u32_e32 v182, v136, v147
	v_add_u32_e32 v186, v136, v145
	ds_read_b128 v[136:139], v182
	ds_read_b128 v[140:143], v182 offset:32
	ds_read_b128 v[166:169], v186 offset:18432
	ds_read_b128 v[170:173], v186 offset:18464
	ds_read_b128 v[174:177], v182 offset:64
	ds_read_b128 v[178:181], v186 offset:18496
	ds_read_b128 v[182:185], v182 offset:96
	ds_read_b128 v[186:189], v186 offset:18528
	s_waitcnt lgkmcnt(5)
	v_mfma_f32_32x32x16_bf16 v[0:15], v[136:139], v[166:169], v[0:15]
	s_waitcnt lgkmcnt(4)
	v_mfma_f32_32x32x16_bf16 v[0:15], v[140:143], v[170:173], v[0:15]
	s_waitcnt lgkmcnt(2)
	v_mfma_f32_32x32x16_bf16 v[0:15], v[174:177], v[178:181], v[0:15]
	s_waitcnt lgkmcnt(0)
	v_mfma_f32_32x32x16_bf16 v[0:15], v[182:185], v[186:189], v[0:15]
	s_nop 11
	v_cvt_pk_bf16_f32 v136, v0, v1
	v_cvt_pk_bf16_f32 v137, v2, v3
	v_cvt_pk_bf16_f32 v138, v4, v5
	v_cvt_pk_bf16_f32 v139, v6, v7
	ds_write2_b64 v162, v[136:137], v[138:139] offset1:2
	v_cvt_pk_bf16_f32 v136, v8, v9
	v_cvt_pk_bf16_f32 v137, v10, v11
	v_cvt_pk_bf16_f32 v138, v12, v13
	v_cvt_pk_bf16_f32 v139, v14, v15
	ds_write2_b64 v162, v[136:137], v[138:139] offset0:4 offset1:6
	ds_read_b128 v[136:139], v164
	ds_read_b128 v[140:143], v164 offset:4352
	ds_read_b128 v[166:169], v164 offset:64
	ds_read_b128 v[170:173], v164 offset:4416
	ds_read_b128 v[174:177], v164 offset:128
	ds_read_b128 v[178:181], v164 offset:4480
	ds_read_b128 v[182:185], v164 offset:192
	ds_read_b128 v[186:189], v164 offset:4544
	s_waitcnt vmcnt(23) lgkmcnt(7)
	v_mfma_f32_16x16x32_bf16 v[136:139], v[116:119], v[136:139], 0
	s_waitcnt lgkmcnt(6)
	v_mfma_f32_16x16x32_bf16 v[116:119], v[116:119], v[140:143], 0
	s_waitcnt vmcnt(22) lgkmcnt(5)
	v_mfma_f32_16x16x32_bf16 v[136:139], v[112:115], v[166:169], v[136:139]
	s_waitcnt lgkmcnt(4)
	v_mfma_f32_16x16x32_bf16 v[112:115], v[112:115], v[170:173], v[116:119]
	s_waitcnt vmcnt(21) lgkmcnt(3)
	v_mfma_f32_16x16x32_bf16 v[116:119], v[108:111], v[174:177], v[136:139]
	s_waitcnt lgkmcnt(2)
	v_mfma_f32_16x16x32_bf16 v[108:111], v[108:111], v[178:181], v[112:115]
	s_waitcnt vmcnt(20) lgkmcnt(1)
	v_mfma_f32_16x16x32_bf16 v[116:119], v[104:107], v[182:185], v[116:119]
	s_waitcnt lgkmcnt(0)
	v_mfma_f32_16x16x32_bf16 v[104:107], v[104:107], v[186:189], v[108:111]
	s_nop 5
	v_mul_f32_e32 v116, 0x3db504f3, v116
	s_nop 0
	v_mul_f32_e32 v104, 0x3db504f3, v104
	v_mul_f32_e32 v112, 0x3db504f3, v117
	ds_write2_b32 v163, v116, v104 offset1:16
	v_mul_f32_e32 v104, 0x3db504f3, v105
	v_mul_f32_e32 v113, 0x3db504f3, v118
	ds_write2_b32 v163, v112, v104 offset0:65 offset1:81
	v_mul_f32_e32 v104, 0x3db504f3, v106
	v_mul_f32_e32 v114, 0x3db504f3, v119
	ds_write2_b32 v163, v113, v104 offset0:130 offset1:146
	v_mul_f32_e32 v104, 0x3db504f3, v107
	ds_write2_b32 v163, v114, v104 offset0:195 offset1:211
	ds_read2_b32 v[110:111], v165 offset1:1
	ds_read2_b32 v[108:109], v165 offset0:2 offset1:3
	ds_read2_b32 v[106:107], v165 offset0:4 offset1:5
	ds_read2_b32 v[104:105], v165 offset0:6 offset1:7
	s_waitcnt lgkmcnt(3)
	v_pk_mul_f32 v[112:113], v[110:111], v[110:111]
	s_waitcnt lgkmcnt(2)
	v_pk_mul_f32 v[114:115], v[108:109], v[108:109]
	v_add_f32_e32 v112, v112, v113
	v_add_f32_e32 v112, v112, v114
	s_waitcnt lgkmcnt(1)
	v_pk_mul_f32 v[116:117], v[106:107], v[106:107]
	v_add_f32_e32 v112, v112, v115
	v_add_f32_e32 v112, v112, v116
	s_waitcnt lgkmcnt(0)
	v_pk_mul_f32 v[118:119], v[104:105], v[104:105]
	v_add_f32_e32 v112, v112, v117
	v_add_f32_e32 v112, v112, v118
	v_add_f32_e32 v112, v112, v119
	s_nop 1
	v_add_f32_dpp v112, v112, v112 quad_perm:[1,0,3,2] row_mask:0xf bank_mask:0xf bound_ctrl:1
	s_nop 1
	v_add_f32_dpp v112, v112, v112 quad_perm:[2,3,0,1] row_mask:0xf bank_mask:0xf bound_ctrl:1
	s_nop 1
	v_mov_b32_dpp v113, v112 row_half_mirror row_mask:0xf bank_mask:0xf bound_ctrl:1
	s_and_saveexec_b64 s[8:9], s[4:5]
	s_cbranch_execz .LBB0_1085
	v_add_f32_e32 v114, v112, v113
	v_add_co_u32_e32 v112, vcc, 0x1a902000, v134
	s_nop 1
	v_addc_co_u32_e32 v113, vcc, 0, v135, vcc
	global_store_dword v[112:113], v114, off
	s_branch .LBB0_1085
